# speedup vs baseline: 1.0043x; 1.0012x over previous
; __device__ __forceinline__ int crow(int r, int hi) { return (r & 3) + 8 * (r >> 2) + 4 * hi; }
; __device__ __forceinline__ void attn_stream(const u16* __restrict__ Qb, const u16* __restrict__ Kh, const u16* __restrict__ Vh,
;                                             int seq, char* lds, f32x16 (&o)[4]) {
;     ...
;   if (hi == 0) li_l[r32] = l_reg;
;   asm volatile("s_waitcnt lgkmcnt(0)" ::: "memory");
; #pragma unroll
;   for (int r = 0; r < 16; ++r) { const float rl = __builtin_amdgcn_rcpf(li_l[crow(r, hi)]);
; #pragma unroll
;     for (int d0 = 0; d0 < 4; ++d0) o[d0][r] *= rl; }
; __device__ __forceinline__ void phase3(const Params& p, char* shm) {
;     ...
;     { const f32x4* o1p = reinterpret_cast<const f32x4*>(o1s + tid * 64);
; #pragma unroll
;       for (int d0 = 0; d0 < 4; ++d0)
; #pragma unroll
;         for (int q = 0; q < 4; ++q) { const f32x4 v1 = o1p[d0 * 4 + q];
; #pragma unroll
;           for (int e = 0; e < 4; ++e) o[d0][q * 4 + e] = v1[e] - lam * o[d0][q * 4 + e]; } }
;     float sw[4];
; #pragma unroll
;     for (int d0 = 0; d0 < 4; ++d0) sw[d0] = p.subln[d0 * 32 + r32] * 0.8f;
;     char* const otb = shm + ((wid * 32 + 4 * hi) * OT_LD + r32) * 2;
; #pragma unroll
;     for (int r = 0; r < 16; ++r) {
;       float ss = 0.f;
; #pragma unroll
;       for (int d0 = 0; d0 < 4; ++d0) ss += o[d0][r] * o[d0][r];
;       ss += __shfl_xor(ss, 1); ss += __shfl_xor(ss, 2); ss += __shfl_xor(ss, 4); ss += __shfl_xor(ss, 8); ss += __shfl_xor(ss, 16);
;       const float rstd = rsqrtf(ss * (1.f / 128.f) + 1e-6f);
.LBB0_401:
	s_or_b64 exec, exec, s[6:7]
	s_and_saveexec_b64 s[0:1], s[4:5]
	ds_write_b32 v212, v192
	s_or_b64 exec, exec, s[0:1]
	s_waitcnt lgkmcnt(0)
	v_add_u32_e32 v66, v204, v190
	v_mov_b32_e32 v131, v1
	ds_read_b128 v[138:141], v66
	s_waitcnt vmcnt(2)
	ds_read_b128 v[144:147], v66 offset:32
	s_waitcnt vmcnt(1)
	ds_read_b128 v[148:151], v66 offset:64
	ds_read_b128 v[152:155], v66 offset:96
	s_waitcnt lgkmcnt(0)
	s_barrier
	v_mov_b32_e32 v156, v2
	v_lshrrev_b32_e32 v252, 6, v131
	v_and_b32_e32 v253, 63, v131
	v_lshlrev_b32_e32 v252, 14, v252
	v_lshl_add_u32 v252, v253, 4, v252
	v_add_u32_e32 v253, 0x1000, v252
	v_add_u32_e32 v254, 0x2000, v252
	v_add_u32_e32 v255, 0x3000, v252
	global_load_dwordx4 v[118:121], v252, s[16:17]
	global_load_dwordx4 v[126:129], v253, s[16:17]
	global_load_dwordx4 v[114:117], v254, s[16:17]
	global_load_dwordx4 v[122:125], v255, s[16:17]
	global_load_dwordx4 v[110:113], v252, s[16:17] offset:1024
	global_load_dwordx4 v[106:109], v253, s[16:17] offset:1024
	global_load_dwordx4 v[102:105], v254, s[16:17] offset:1024
	global_load_dwordx4 v[98:101], v255, s[16:17] offset:1024
	v_and_b32_e32 v143, 31, v131
	v_lshlrev_b32_e32 v68, 2, v143
	global_load_dword v161, v68, s[14:15]
	global_load_dword v163, v68, s[14:15] offset:128
	v_and_b32_e32 v67, 64, v203
	v_xor_b32_e32 v66, 1, v203
	v_add_u32_e32 v2, 64, v67
	v_xor_b32_e32 v69, 2, v203
	v_cmp_lt_i32_e32 vcc, v66, v2
	v_xor_b32_e32 v70, 4, v203
	s_waitcnt vmcnt(10)
	v_mov_b32_e32 v159, v18
	v_mov_b32_e32 v18, v35
	v_cndmask_b32_e32 v35, v203, v66, vcc
	v_cmp_lt_i32_e32 vcc, v69, v2
	global_load_dword v165, v68, s[14:15] offset:256
	global_load_dword v168, v68, s[14:15] offset:384
	v_xor_b32_e32 v68, 8, v203
	v_cndmask_b32_e32 v66, v203, v69, vcc
	v_cmp_lt_i32_e32 vcc, v70, v2
	v_xor_b32_e32 v71, 16, v203
	v_mov_b32_e32 v157, v50
	v_cndmask_b32_e32 v67, v203, v70, vcc
	v_cmp_lt_i32_e32 vcc, v68, v2
	v_mov_b32_e32 v50, v3
	v_lshrrev_b32_e32 v3, 3, v131
	v_cndmask_b32_e32 v68, v203, v68, vcc
	v_cmp_lt_i32_e32 vcc, v71, v2
	v_mov_b32_e32 v158, v34
	v_lshrrev_b32_e32 v34, 1, v131
	v_cndmask_b32_e32 v2, v203, v71, vcc
	v_and_b32_e32 v69, 4, v3
	v_lshlrev_b32_e32 v3, 2, v2
	v_and_or_b32 v2, v34, s69, v69
	v_mul_lo_u32 v169, v2, s70
	v_rcp_f32_e32 v2, v138
	v_rcp_f32_e32 v162, v140
	v_rcp_f32_e32 v140, v146
	v_rcp_f32_e32 v138, v147
	v_pk_mul_f32 v[146:147], v[156:157], v[2:3] op_sel_hi:[1,0]
	v_pk_mul_f32 v[156:157], v[158:159], v[2:3] op_sel_hi:[1,0]
	v_lshlrev_b32_e32 v137, 2, v35
	v_lshlrev_b32_e32 v135, 2, v66
	v_lshlrev_b32_e32 v133, 2, v67
	v_lshlrev_b32_e32 v35, 2, v68
	v_rcp_f32_e32 v164, v141
	v_rcp_f32_e32 v160, v139
	v_or_b32_e32 v139, v169, v143
	v_rcp_f32_e32 v136, v148
	v_rcp_f32_e32 v134, v149
	v_rcp_f32_e32 v132, v150
	v_rcp_f32_e32 v130, v151
	global_load_dwordx4 v[74:77], v252, s[16:17] offset:3072
	global_load_dwordx4 v[90:93], v252, s[16:17] offset:2048
	global_load_dwordx4 v[78:81], v253, s[16:17] offset:3072
	global_load_dwordx4 v[94:97], v253, s[16:17] offset:2048
	global_load_dwordx4 v[66:69], v254, s[16:17] offset:3072
	global_load_dwordx4 v[82:85], v254, s[16:17] offset:2048
	global_load_dwordx4 v[70:73], v255, s[16:17] offset:3072
	s_nop 0
	global_load_dwordx4 v[86:89], v255, s[16:17] offset:2048
	v_rcp_f32_e32 v144, v144
	v_rcp_f32_e32 v142, v145
	s_waitcnt vmcnt(19)
	v_mov_b32_e32 v158, v118
	s_waitcnt vmcnt(18)
	v_mov_b32_e32 v159, v126
	s_waitcnt vmcnt(17)
	v_mov_b32_e32 v166, v114
	s_waitcnt vmcnt(16)
	v_mov_b32_e32 v167, v122
	v_pk_fma_f32 v[146:147], v[188:189], v[146:147], v[158:159] neg_lo:[1,0,0] neg_hi:[1,0,0]
	v_pk_fma_f32 v[156:157], v[188:189], v[156:157], v[166:167] neg_lo:[1,0,0] neg_hi:[1,0,0]
	v_pk_mul_f32 v[158:159], v[146:147], v[146:147]
	v_pk_mul_f32 v[166:167], v[156:157], v[156:157]
	v_add_f32_e32 v2, v158, v159
	v_add_f32_e32 v2, v2, v166
	v_add_f32_e32 v2, v2, v167
	s_nop 1
	v_mov_b32_dpp v34, v2 quad_perm:[1,0,3,2] row_mask:0xf bank_mask:0xf
	s_waitcnt vmcnt(11)
	v_pk_mul_f32 v[148:149], v[50:51], v[160:161] op_sel_hi:[1,0]
	v_pk_mul_f32 v[150:151], v[18:19], v[160:161] op_sel_hi:[1,0]
	v_mul_f32_e32 v51, 0x3f4ccccd, v161
	v_rcp_f32_e32 v118, v152
	s_waitcnt lgkmcnt(0)
	v_add_f32_e32 v122, v2, v34
	s_nop 1
	v_mov_b32_dpp v126, v122 quad_perm:[2,3,0,1] row_mask:0xf bank_mask:0xf
	v_rcp_f32_e32 v114, v153
	v_mov_b32_e32 v152, v116
	v_mov_b32_e32 v153, v124
	s_waitcnt vmcnt(10)
	v_mul_f32_e32 v50, 0x3f4ccccd, v163
	s_waitcnt lgkmcnt(0)
	v_add_f32_e32 v122, v122, v126
	s_nop 1
	v_mov_b32_dpp v126, v122 row_half_mirror row_mask:0xf bank_mask:0xf
	s_waitcnt vmcnt(9)
	v_mul_f32_e32 v19, 0x3f4ccccd, v165
	s_waitcnt vmcnt(8)
	v_mul_f32_e32 v18, 0x3f4ccccd, v168
	v_mov_b32_e32 v124, v117
	v_mov_b32_e32 v117, v22
	s_waitcnt lgkmcnt(0)
	v_add_f32_e32 v141, v122, v126
	s_nop 1
	v_mov_b32_dpp v143, v141 row_mirror row_mask:0xf bank_mask:0xf
	v_mov_b32_e32 v122, v115
	v_mov_b32_e32 v126, v119
	v_pk_fma_f32 v[126:127], v[188:189], v[148:149], v[126:127] neg_lo:[1,0,0] neg_hi:[1,0,0]
	v_pk_fma_f32 v[122:123], v[188:189], v[150:151], v[122:123] neg_lo:[1,0,0] neg_hi:[1,0,0]
	s_waitcnt lgkmcnt(0)
	v_add_f32_e32 v115, v141, v143
	ds_bpermute_b32 v119, v3, v115
	v_pk_mul_f32 v[148:149], v[126:127], v[126:127]
	v_pk_mul_f32 v[150:151], v[122:123], v[122:123]
	v_rcp_f32_e32 v34, v154
	v_rcp_f32_e32 v2, v155
	s_waitcnt lgkmcnt(0)
	v_add_f32_e32 v115, v115, v119
	v_add_f32_e32 v119, v148, v149
	v_add_f32_e32 v119, v119, v150
	v_add_f32_e32 v119, v119, v151
	v_fmamk_f32 v115, v115, 0x3c000000, v187
	s_nop 1
	v_mov_b32_dpp v141, v119 quad_perm:[1,0,3,2] row_mask:0xf bank_mask:0xf
	v_mul_f32_e32 v143, 0x4b800000, v115
	v_cmp_gt_f32_e32 vcc, s71, v115
	v_mov_b32_e32 v148, v120
	v_mov_b32_e32 v149, v128
	v_cndmask_b32_e32 v115, v115, v143, vcc
	v_rsq_f32_e32 v143, v115
	s_waitcnt lgkmcnt(0)
; __device__ __forceinline__ u16 f2bf(float f) { return (u16)(cvtpk(f, f) & 0xffffu); }
; __device__ __forceinline__ void phase3(const Params& p, char* shm) {
;     ...
;     for (int r = 0; r < 16; ++r) {
;       float ss = 0.f;
; #pragma unroll
;       for (int d0 = 0; d0 < 4; ++d0) ss += o[d0][r] * o[d0][r];
;       ss += __shfl_xor(ss, 1); ss += __shfl_xor(ss, 2); ss += __shfl_xor(ss, 4); ss += __shfl_xor(ss, 8); ss += __shfl_xor(ss, 16);
;       const float rstd = rsqrtf(ss * (1.f / 128.f) + 1e-6f);
; #pragma unroll
;       for (int d0 = 0; d0 < 4; ++d0) *(u16*)(otb + (((r & 3) + 8 * (r >> 2)) * OT_LD + d0 * 32) * 2) = f2bf(o[d0][r] * rstd * sw[d0]);
	v_add_f32_e32 v119, v119, v141
	s_nop 1
	v_mov_b32_dpp v141, v119 quad_perm:[2,3,0,1] row_mask:0xf bank_mask:0xf
	v_lshl_add_u32 v115, v139, 1, 0
	v_mul_f32_e32 v139, 0x45800000, v143
	v_cndmask_b32_e32 v139, v143, v139, vcc
	v_mul_f32_e32 v143, v146, v139
	v_mul_f32_e32 v143, v51, v143
	s_waitcnt lgkmcnt(0)
	v_add_f32_e32 v119, v119, v141
	s_nop 0
	v_cvt_pk_bf16_f32 v143, v143, v143
	s_nop 1
	v_mov_b32_dpp v141, v119 row_half_mirror row_mask:0xf bank_mask:0xf
	ds_write_b16 v115, v143
	v_mul_f32_e32 v143, v147, v139
	v_mov_b32_e32 v146, v4
	v_mov_b32_e32 v147, v52
	v_pk_mul_f32 v[146:147], v[146:147], v[162:163] op_sel_hi:[1,0]
	v_mov_b32_e32 v150, v36
	v_mov_b32_e32 v151, v20
	v_pk_fma_f32 v[146:147], v[188:189], v[146:147], v[148:149] neg_lo:[1,0,0] neg_hi:[1,0,0]
	v_pk_mul_f32 v[150:151], v[150:151], v[162:163] op_sel_hi:[1,0]
	v_pk_mul_f32 v[148:149], v[146:147], v[146:147]
	v_pk_fma_f32 v[150:151], v[188:189], v[150:151], v[152:153] neg_lo:[1,0,0] neg_hi:[1,0,0]
	v_add_f32_e32 v4, v148, v149
	v_pk_mul_f32 v[152:153], v[150:151], v[150:151]
	s_waitcnt lgkmcnt(0)
	v_add_f32_e32 v119, v119, v141
	v_add_f32_e32 v4, v4, v152
	s_nop 1
	v_mov_b32_dpp v141, v119 row_mirror row_mask:0xf bank_mask:0xf
	v_add_f32_e32 v4, v4, v153
	s_nop 1
	v_mov_b32_dpp v20, v4 quad_perm:[1,0,3,2] row_mask:0xf bank_mask:0xf
	v_mul_f32_e32 v143, v50, v143
	s_nop 0
	v_cvt_pk_bf16_f32 v143, v143, v143
	s_waitcnt lgkmcnt(0)
	v_add_f32_e32 v119, v119, v141
	ds_bpermute_b32 v141, v3, v119
	s_waitcnt lgkmcnt(0)
	v_add_f32_e32 v4, v4, v20
	s_nop 1
	v_mov_b32_dpp v20, v4 quad_perm:[2,3,0,1] row_mask:0xf bank_mask:0xf
	ds_write_b16 v115, v143 offset:64
	v_mul_f32_e32 v143, v156, v139
	s_waitcnt lgkmcnt(0)
	v_add_f32_e32 v119, v119, v141
	v_fmamk_f32 v119, v119, 0x3c000000, v187
	s_waitcnt lgkmcnt(0)
	v_add_f32_e32 v4, v4, v20
	v_mul_f32_e32 v141, 0x4b800000, v119
	v_cmp_gt_f32_e32 vcc, s71, v119
	s_nop 1
	v_mov_b32_dpp v20, v4 row_half_mirror row_mask:0xf bank_mask:0xf
	v_mul_f32_e32 v139, v157, v139
	v_cndmask_b32_e32 v119, v119, v141, vcc
	v_rsq_f32_e32 v119, v119
	v_mul_f32_e32 v143, v19, v143
	v_mul_f32_e32 v36, v18, v139
	s_nop 0
	v_cvt_pk_bf16_f32 v143, v143, v143
	ds_write_b16 v115, v143 offset:128
	s_nop 0
	v_cvt_pk_bf16_f32 v36, v36, v36
	s_waitcnt lgkmcnt(0)
	v_add_f32_e32 v4, v4, v20
	ds_write_b16 v115, v36 offset:192
	v_mul_f32_e32 v36, 0x45800000, v119
	s_nop 1
	v_mov_b32_dpp v20, v4 row_mirror row_mask:0xf bank_mask:0xf
	v_cndmask_b32_e32 v36, v119, v36, vcc
	v_mul_f32_e32 v52, v126, v36
	v_mul_f32_e32 v52, v51, v52
	s_nop 0
	v_cvt_pk_bf16_f32 v52, v52, v52
	ds_write_b16 v115, v52 offset:272
	v_mul_f32_e32 v52, v127, v36
	s_waitcnt lgkmcnt(0)
	v_add_f32_e32 v4, v4, v20
	v_mul_f32_e32 v52, v50, v52
	ds_bpermute_b32 v20, v3, v4
	s_nop 0
	v_cvt_pk_bf16_f32 v52, v52, v52
	ds_write_b16 v115, v52 offset:336
	v_mul_f32_e32 v52, v122, v36
	v_mul_f32_e32 v52, v19, v52
	s_nop 0
	v_cvt_pk_bf16_f32 v52, v52, v52
	ds_write_b16 v115, v52 offset:400
	s_waitcnt lgkmcnt(0)
	v_add_f32_e32 v4, v4, v20
	v_mov_b32_e32 v52, v5
	v_fmamk_f32 v119, v4, 0x3c000000, v187
	v_pk_mul_f32 v[4:5], v[52:53], v[164:165] op_sel_hi:[1,0]
	v_mov_b32_e32 v128, v121
	v_mov_b32_e32 v20, v37
	v_mul_f32_e32 v36, v123, v36
	v_pk_fma_f32 v[4:5], v[188:189], v[4:5], v[128:129] neg_lo:[1,0,0] neg_hi:[1,0,0]
	v_pk_mul_f32 v[20:21], v[20:21], v[164:165] op_sel_hi:[1,0]
	v_mul_f32_e32 v36, v18, v36
	v_pk_mul_f32 v[52:53], v[4:5], v[4:5]
	v_pk_fma_f32 v[20:21], v[188:189], v[20:21], v[124:125] neg_lo:[1,0,0] neg_hi:[1,0,0]
	s_nop 0
	v_cvt_pk_bf16_f32 v116, v36, v36
	v_add_f32_e32 v52, v52, v53
	v_pk_mul_f32 v[36:37], v[20:21], v[20:21]
	v_cmp_gt_f32_e32 vcc, s71, v119
	v_add_f32_e32 v36, v52, v36
	v_add_f32_e32 v36, v36, v37
	s_nop 1
	v_mov_b32_dpp v37, v36 quad_perm:[1,0,3,2] row_mask:0xf bank_mask:0xf
	v_mul_f32_e32 v52, 0x4b800000, v119
	v_cndmask_b32_e32 v52, v119, v52, vcc
	v_rsq_f32_e32 v52, v52
	ds_write_b16 v115, v116 offset:464
	s_waitcnt lgkmcnt(0)
	v_add_f32_e32 v36, v36, v37
	s_nop 1
	v_mov_b32_dpp v37, v36 quad_perm:[2,3,0,1] row_mask:0xf bank_mask:0xf
	v_mul_f32_e32 v53, 0x45800000, v52
	v_cndmask_b32_e32 v52, v52, v53, vcc
	v_mul_f32_e32 v53, v146, v52
	v_mul_f32_e32 v53, v51, v53
	s_waitcnt lgkmcnt(0)
	v_add_f32_e32 v36, v36, v37
	s_nop 1
	v_mov_b32_dpp v37, v36 row_half_mirror row_mask:0xf bank_mask:0xf
	s_nop 0
	v_cvt_pk_bf16_f32 v53, v53, v53
	ds_write_b16 v115, v53 offset:544
	v_mul_f32_e32 v53, v147, v52
	v_mul_f32_e32 v53, v50, v53
	s_waitcnt lgkmcnt(0)
	v_add_f32_e32 v36, v36, v37
	s_nop 1
	v_mov_b32_dpp v37, v36 row_mirror row_mask:0xf bank_mask:0xf
	s_nop 0
	v_cvt_pk_bf16_f32 v53, v53, v53
	ds_write_b16 v115, v53 offset:608
	v_mul_f32_e32 v53, v150, v52
	v_mul_f32_e32 v53, v19, v53
	s_waitcnt lgkmcnt(0)
	v_add_f32_e32 v36, v36, v37
	ds_bpermute_b32 v37, v3, v36
	s_nop 0
	v_cvt_pk_bf16_f32 v53, v53, v53
	ds_write_b16 v115, v53 offset:672
	v_mul_f32_e32 v119, v151, v52
	v_mov_b32_e32 v52, v110
	s_waitcnt lgkmcnt(0)
	v_add_f32_e32 v36, v36, v37
	v_fmamk_f32 v36, v36, 0x3c000000, v187
	v_mul_f32_e32 v37, 0x4b800000, v36
	v_cmp_gt_f32_e32 vcc, s71, v36
	v_mov_b32_e32 v53, v106
	v_mov_b32_e32 v116, v38
	v_cndmask_b32_e32 v36, v36, v37, vcc
	v_rsq_f32_e32 v122, v36
	v_mov_b32_e32 v36, v6
	v_mov_b32_e32 v37, v54
	v_pk_mul_f32 v[36:37], v[36:37], v[144:145] op_sel_hi:[1,0]
	v_pk_mul_f32 v[116:117], v[116:117], v[144:145] op_sel_hi:[1,0]
	v_pk_fma_f32 v[36:37], v[188:189], v[36:37], v[52:53] neg_lo:[1,0,0] neg_hi:[1,0,0]
	v_mov_b32_e32 v120, v102
	v_mov_b32_e32 v121, v98
	v_pk_mul_f32 v[52:53], v[36:37], v[36:37]
	v_pk_fma_f32 v[116:117], v[188:189], v[116:117], v[120:121] neg_lo:[1,0,0] neg_hi:[1,0,0]
	v_add_f32_e32 v6, v52, v53
	v_pk_mul_f32 v[120:121], v[116:117], v[116:117]
	v_mul_f32_e32 v38, v18, v119
	v_add_f32_e32 v6, v6, v120
	v_add_f32_e32 v6, v6, v121
	s_nop 1
	v_mov_b32_dpp v22, v6 quad_perm:[1,0,3,2] row_mask:0xf bank_mask:0xf
	s_nop 0
	v_cvt_pk_bf16_f32 v38, v38, v38
	ds_write_b16 v115, v38 offset:736
	v_mul_f32_e32 v38, 0x45800000, v122
	v_cndmask_b32_e32 v38, v122, v38, vcc
	s_waitcnt lgkmcnt(0)
; __device__ __forceinline__ u16 f2bf(float f) { return (u16)(cvtpk(f, f) & 0xffffu); }
; __device__ __forceinline__ void phase3(const Params& p, char* shm) {
;     ...
;     for (int r = 0; r < 16; ++r) {
;       float ss = 0.f;
; #pragma unroll
;       for (int d0 = 0; d0 < 4; ++d0) ss += o[d0][r] * o[d0][r];
;       ss += __shfl_xor(ss, 1); ss += __shfl_xor(ss, 2); ss += __shfl_xor(ss, 4); ss += __shfl_xor(ss, 8); ss += __shfl_xor(ss, 16);
;       const float rstd = rsqrtf(ss * (1.f / 128.f) + 1e-6f);
; #pragma unroll
;       for (int d0 = 0; d0 < 4; ++d0) *(u16*)(otb + (((r & 3) + 8 * (r >> 2)) * OT_LD + d0 * 32) * 2) = f2bf(o[d0][r] * rstd * sw[d0]);
	v_add_f32_e32 v6, v6, v22
	s_nop 1
	v_mov_b32_dpp v22, v6 quad_perm:[2,3,0,1] row_mask:0xf bank_mask:0xf
	v_mul_f32_e32 v4, v4, v38
	v_mul_f32_e32 v4, v51, v4
	s_nop 0
	v_cvt_pk_bf16_f32 v4, v4, v4
	ds_write_b16 v115, v4 offset:816
	s_waitcnt lgkmcnt(0)
	v_add_f32_e32 v6, v6, v22
	s_nop 1
	v_mov_b32_dpp v22, v6 row_half_mirror row_mask:0xf bank_mask:0xf
	v_mul_f32_e32 v4, v5, v38
	v_mul_f32_e32 v4, v50, v4
	s_nop 0
	v_cvt_pk_bf16_f32 v4, v4, v4
	ds_write_b16 v115, v4 offset:880
	s_waitcnt lgkmcnt(0)
	v_add_f32_e32 v5, v6, v22
	s_nop 1
	v_mov_b32_dpp v6, v5 row_mirror row_mask:0xf bank_mask:0xf
	v_mul_f32_e32 v4, v20, v38
	v_mul_f32_e32 v4, v19, v4
	s_nop 0
	v_cvt_pk_bf16_f32 v4, v4, v4
	ds_write_b16 v115, v4 offset:944
	s_waitcnt lgkmcnt(0)
	v_add_f32_e32 v5, v5, v6
	ds_bpermute_b32 v6, v3, v5
	v_mul_f32_e32 v4, v21, v38
	v_mul_f32_e32 v4, v18, v4
	s_nop 0
	v_cvt_pk_bf16_f32 v38, v4, v4
	v_mov_b32_e32 v54, v7
	s_waitcnt lgkmcnt(0)
	v_add_f32_e32 v4, v5, v6
	v_fmamk_f32 v52, v4, 0x3c000000, v187
	v_pk_mul_f32 v[4:5], v[54:55], v[142:143] op_sel_hi:[1,0]
	v_mov_b32_e32 v106, v111
	v_mov_b32_e32 v22, v39
	v_pk_fma_f32 v[4:5], v[188:189], v[4:5], v[106:107] neg_lo:[1,0,0] neg_hi:[1,0,0]
	v_pk_mul_f32 v[20:21], v[22:23], v[142:143] op_sel_hi:[1,0]
	v_mov_b32_e32 v98, v103
	v_pk_mul_f32 v[6:7], v[4:5], v[4:5]
	v_pk_fma_f32 v[20:21], v[188:189], v[20:21], v[98:99] neg_lo:[1,0,0] neg_hi:[1,0,0]
	v_add_f32_e32 v6, v6, v7
	v_pk_mul_f32 v[22:23], v[20:21], v[20:21]
	v_cmp_gt_f32_e32 vcc, s71, v52
	v_add_f32_e32 v6, v6, v22
	v_add_f32_e32 v6, v6, v23
	s_nop 1
	v_mov_b32_dpp v7, v6 quad_perm:[1,0,3,2] row_mask:0xf bank_mask:0xf
	v_mul_f32_e32 v22, 0x4b800000, v52
	v_cndmask_b32_e32 v22, v52, v22, vcc
	v_rsq_f32_e32 v22, v22
	ds_write_b16 v115, v38 offset:1008
	s_waitcnt lgkmcnt(0)
	v_add_f32_e32 v6, v6, v7
	s_nop 1
	v_mov_b32_dpp v7, v6 quad_perm:[2,3,0,1] row_mask:0xf bank_mask:0xf
	v_mul_f32_e32 v23, 0x45800000, v22
	v_cndmask_b32_e32 v22, v22, v23, vcc
	v_mul_f32_e32 v23, v36, v22
	v_mul_f32_e32 v23, v51, v23
	s_waitcnt lgkmcnt(0)
	v_add_f32_e32 v6, v6, v7
	s_nop 1
	v_mov_b32_dpp v7, v6 row_half_mirror row_mask:0xf bank_mask:0xf
	s_nop 0
	v_cvt_pk_bf16_f32 v23, v23, v23
	ds_write_b16 v115, v23 offset:2176
	v_mul_f32_e32 v23, v37, v22
	v_mul_f32_e32 v23, v50, v23
	s_waitcnt lgkmcnt(0)
	v_add_f32_e32 v6, v6, v7
	s_nop 1
	v_mov_b32_dpp v7, v6 row_mirror row_mask:0xf bank_mask:0xf
	s_nop 0
	v_cvt_pk_bf16_f32 v23, v23, v23
	ds_write_b16 v115, v23 offset:2240
	v_mul_f32_e32 v23, v116, v22
	v_mul_f32_e32 v23, v19, v23
	s_waitcnt lgkmcnt(0)
	v_add_f32_e32 v6, v6, v7
	ds_bpermute_b32 v7, v3, v6
	s_nop 0
	v_cvt_pk_bf16_f32 v23, v23, v23
	ds_write_b16 v115, v23 offset:2304
	v_mul_f32_e32 v52, v117, v22
	v_mov_b32_e32 v22, v112
	s_waitcnt lgkmcnt(0)
	v_add_f32_e32 v6, v6, v7
	v_fmamk_f32 v6, v6, 0x3c000000, v187
	v_mul_f32_e32 v7, 0x4b800000, v6
	v_cmp_gt_f32_e32 vcc, s71, v6
	v_mov_b32_e32 v23, v108
	v_mov_b32_e32 v36, v40
	v_cndmask_b32_e32 v6, v6, v7, vcc
	v_rsq_f32_e32 v53, v6
	v_mov_b32_e32 v6, v8
	v_mov_b32_e32 v7, v56
	v_pk_mul_f32 v[6:7], v[6:7], v[140:141] op_sel_hi:[1,0]
	v_mov_b32_e32 v37, v24
	v_pk_fma_f32 v[6:7], v[188:189], v[6:7], v[22:23] neg_lo:[1,0,0] neg_hi:[1,0,0]
	v_pk_mul_f32 v[36:37], v[36:37], v[140:141] op_sel_hi:[1,0]
	v_mov_b32_e32 v38, v104
	v_mov_b32_e32 v39, v100
	v_pk_mul_f32 v[22:23], v[6:7], v[6:7]
	v_pk_fma_f32 v[36:37], v[188:189], v[36:37], v[38:39] neg_lo:[1,0,0] neg_hi:[1,0,0]
	v_add_f32_e32 v8, v22, v23
	v_pk_mul_f32 v[38:39], v[36:37], v[36:37]
	v_mul_f32_e32 v23, v18, v52
	v_add_f32_e32 v8, v8, v38
	v_add_f32_e32 v8, v8, v39
	s_nop 1
	v_mov_b32_dpp v22, v8 quad_perm:[1,0,3,2] row_mask:0xf bank_mask:0xf
	s_nop 0
	v_cvt_pk_bf16_f32 v23, v23, v23
	ds_write_b16 v115, v23 offset:2368
	v_mul_f32_e32 v23, 0x45800000, v53
	v_cndmask_b32_e32 v23, v53, v23, vcc
	s_waitcnt lgkmcnt(0)
	v_add_f32_e32 v8, v8, v22
	s_nop 1
	v_mov_b32_dpp v22, v8 quad_perm:[2,3,0,1] row_mask:0xf bank_mask:0xf
	v_mul_f32_e32 v4, v4, v23
	v_mul_f32_e32 v4, v51, v4
	s_nop 0
	v_cvt_pk_bf16_f32 v4, v4, v4
	ds_write_b16 v115, v4 offset:2448
	s_waitcnt lgkmcnt(0)
	v_add_f32_e32 v8, v8, v22
	s_nop 1
	v_mov_b32_dpp v22, v8 row_half_mirror row_mask:0xf bank_mask:0xf
	v_mul_f32_e32 v4, v5, v23
	v_mul_f32_e32 v4, v50, v4
	s_nop 0
	v_cvt_pk_bf16_f32 v4, v4, v4
	ds_write_b16 v115, v4 offset:2512
	s_waitcnt lgkmcnt(0)
	v_add_f32_e32 v5, v8, v22
	s_nop 1
	v_mov_b32_dpp v8, v5 row_mirror row_mask:0xf bank_mask:0xf
	v_mul_f32_e32 v4, v20, v23
	v_mul_f32_e32 v4, v19, v4
	s_nop 0
	v_cvt_pk_bf16_f32 v4, v4, v4
	ds_write_b16 v115, v4 offset:2576
	s_waitcnt lgkmcnt(0)
	v_add_f32_e32 v5, v5, v8
	ds_bpermute_b32 v8, v3, v5
	v_mul_f32_e32 v4, v21, v23
	v_mul_f32_e32 v4, v18, v4
	s_nop 0
	v_cvt_pk_bf16_f32 v38, v4, v4
	v_mov_b32_e32 v56, v9
	s_waitcnt lgkmcnt(0)
	v_add_f32_e32 v4, v5, v8
	v_fmamk_f32 v39, v4, 0x3c000000, v187
	v_pk_mul_f32 v[4:5], v[56:57], v[138:139] op_sel_hi:[1,0]
	v_mov_b32_e32 v108, v113
	v_mov_b32_e32 v24, v41
	v_pk_fma_f32 v[4:5], v[188:189], v[4:5], v[108:109] neg_lo:[1,0,0] neg_hi:[1,0,0]
	v_pk_mul_f32 v[20:21], v[24:25], v[138:139] op_sel_hi:[1,0]
	v_mov_b32_e32 v100, v105
	v_pk_mul_f32 v[8:9], v[4:5], v[4:5]
	v_pk_fma_f32 v[20:21], v[188:189], v[20:21], v[100:101] neg_lo:[1,0,0] neg_hi:[1,0,0]
	v_add_f32_e32 v8, v8, v9
	v_pk_mul_f32 v[22:23], v[20:21], v[20:21]
	v_cmp_gt_f32_e32 vcc, s71, v39
	v_add_f32_e32 v8, v8, v22
	v_add_f32_e32 v8, v8, v23
	s_nop 1
	v_mov_b32_dpp v9, v8 quad_perm:[1,0,3,2] row_mask:0xf bank_mask:0xf
	v_mul_f32_e32 v22, 0x4b800000, v39
	v_cndmask_b32_e32 v22, v39, v22, vcc
	v_rsq_f32_e32 v22, v22
	ds_write_b16 v115, v38 offset:2640
	s_waitcnt lgkmcnt(0)
; __device__ __forceinline__ u16 f2bf(float f) { return (u16)(cvtpk(f, f) & 0xffffu); }
; __device__ __forceinline__ void phase3(const Params& p, char* shm) {
;     ...
;     for (int r = 0; r < 16; ++r) {
;       float ss = 0.f;
; #pragma unroll
;       for (int d0 = 0; d0 < 4; ++d0) ss += o[d0][r] * o[d0][r];
;       ss += __shfl_xor(ss, 1); ss += __shfl_xor(ss, 2); ss += __shfl_xor(ss, 4); ss += __shfl_xor(ss, 8); ss += __shfl_xor(ss, 16);
;       const float rstd = rsqrtf(ss * (1.f / 128.f) + 1e-6f);
; #pragma unroll
;       for (int d0 = 0; d0 < 4; ++d0) *(u16*)(otb + (((r & 3) + 8 * (r >> 2)) * OT_LD + d0 * 32) * 2) = f2bf(o[d0][r] * rstd * sw[d0]);
;     }
	v_add_f32_e32 v8, v8, v9
	s_nop 1
	v_mov_b32_dpp v9, v8 quad_perm:[2,3,0,1] row_mask:0xf bank_mask:0xf
	v_mul_f32_e32 v23, 0x45800000, v22
	v_cndmask_b32_e32 v22, v22, v23, vcc
	v_mul_f32_e32 v6, v6, v22
	v_mul_f32_e32 v6, v51, v6
	s_waitcnt lgkmcnt(0)
	v_add_f32_e32 v8, v8, v9
	s_nop 1
	v_mov_b32_dpp v9, v8 row_half_mirror row_mask:0xf bank_mask:0xf
	s_nop 0
	v_cvt_pk_bf16_f32 v6, v6, v6
	ds_write_b16 v115, v6 offset:2720
	v_mul_f32_e32 v6, v7, v22
	v_mul_f32_e32 v6, v50, v6
	s_waitcnt lgkmcnt(0)
	v_add_f32_e32 v7, v8, v9
	s_nop 1
	v_mov_b32_dpp v8, v7 row_mirror row_mask:0xf bank_mask:0xf
	s_nop 0
	v_cvt_pk_bf16_f32 v6, v6, v6
	ds_write_b16 v115, v6 offset:2784
	v_mul_f32_e32 v6, v36, v22
	v_mul_f32_e32 v6, v19, v6
	s_waitcnt lgkmcnt(0)
	v_add_f32_e32 v7, v7, v8
	ds_bpermute_b32 v8, v3, v7
	s_nop 0
	v_cvt_pk_bf16_f32 v6, v6, v6
	ds_write_b16 v115, v6 offset:2848
	v_mul_f32_e32 v36, v37, v22
	s_waitcnt vmcnt(4)
	v_mov_b32_e32 v9, v94
	s_waitcnt lgkmcnt(0)
	v_add_f32_e32 v6, v7, v8
	v_fmamk_f32 v6, v6, 0x3c000000, v187
	v_mul_f32_e32 v7, 0x4b800000, v6
	v_cmp_gt_f32_e32 vcc, s71, v6
	v_mov_b32_e32 v8, v90
	v_mov_b32_e32 v22, v42
	v_cndmask_b32_e32 v6, v6, v7, vcc
	v_rsq_f32_e32 v37, v6
	v_mov_b32_e32 v6, v10
	v_mov_b32_e32 v7, v58
	v_pk_mul_f32 v[6:7], v[6:7], v[136:137] op_sel_hi:[1,0]
	v_mov_b32_e32 v23, v26
	v_pk_fma_f32 v[6:7], v[188:189], v[6:7], v[8:9] neg_lo:[1,0,0] neg_hi:[1,0,0]
	v_pk_mul_f32 v[22:23], v[22:23], v[136:137] op_sel_hi:[1,0]
	s_waitcnt vmcnt(2)
	v_mov_b32_e32 v24, v82
	s_waitcnt vmcnt(0)
	v_mov_b32_e32 v25, v86
	v_pk_mul_f32 v[8:9], v[6:7], v[6:7]
	v_pk_fma_f32 v[22:23], v[188:189], v[22:23], v[24:25] neg_lo:[1,0,0] neg_hi:[1,0,0]
	v_add_f32_e32 v8, v8, v9
	v_pk_mul_f32 v[24:25], v[22:23], v[22:23]
	v_mul_f32_e32 v10, v18, v36
	v_add_f32_e32 v8, v8, v24
	v_add_f32_e32 v8, v8, v25
	s_nop 1
	v_mov_b32_dpp v9, v8 quad_perm:[1,0,3,2] row_mask:0xf bank_mask:0xf
	s_nop 0
	v_cvt_pk_bf16_f32 v10, v10, v10
	ds_write_b16 v115, v10 offset:2912
	v_mul_f32_e32 v10, 0x45800000, v37
	v_cndmask_b32_e32 v10, v37, v10, vcc
	s_waitcnt lgkmcnt(0)
	v_add_f32_e32 v8, v8, v9
	s_nop 1
	v_mov_b32_dpp v9, v8 quad_perm:[2,3,0,1] row_mask:0xf bank_mask:0xf
	v_mul_f32_e32 v4, v4, v10
	v_mul_f32_e32 v4, v51, v4
	s_nop 0
	v_cvt_pk_bf16_f32 v4, v4, v4
	ds_write_b16 v115, v4 offset:2992
	s_waitcnt lgkmcnt(0)
	v_add_f32_e32 v8, v8, v9
	s_nop 1
	v_mov_b32_dpp v9, v8 row_half_mirror row_mask:0xf bank_mask:0xf
	v_mul_f32_e32 v4, v5, v10
	v_mul_f32_e32 v4, v50, v4
	s_nop 0
	v_cvt_pk_bf16_f32 v4, v4, v4
	ds_write_b16 v115, v4 offset:3056
	s_waitcnt lgkmcnt(0)
	v_add_f32_e32 v5, v8, v9
	s_nop 1
	v_mov_b32_dpp v8, v5 row_mirror row_mask:0xf bank_mask:0xf
	v_mul_f32_e32 v4, v20, v10
	v_mul_f32_e32 v4, v19, v4
	s_nop 0
	v_cvt_pk_bf16_f32 v4, v4, v4
	ds_write_b16 v115, v4 offset:3120
	s_waitcnt lgkmcnt(0)
	v_add_f32_e32 v5, v5, v8
	ds_bpermute_b32 v8, v3, v5
	v_mul_f32_e32 v4, v21, v10
	v_mul_f32_e32 v4, v18, v4
	s_nop 0
	v_cvt_pk_bf16_f32 v24, v4, v4
	v_mov_b32_e32 v58, v11
	s_waitcnt lgkmcnt(0)
	v_add_f32_e32 v4, v5, v8
	v_fmamk_f32 v25, v4, 0x3c000000, v187
	v_pk_mul_f32 v[4:5], v[58:59], v[134:135] op_sel_hi:[1,0]
	v_mov_b32_e32 v94, v91
	v_mov_b32_e32 v26, v43
	v_pk_fma_f32 v[4:5], v[188:189], v[4:5], v[94:95] neg_lo:[1,0,0] neg_hi:[1,0,0]
	v_pk_mul_f32 v[10:11], v[26:27], v[134:135] op_sel_hi:[1,0]
	v_mov_b32_e32 v86, v83
	v_pk_mul_f32 v[8:9], v[4:5], v[4:5]
	v_pk_fma_f32 v[10:11], v[188:189], v[10:11], v[86:87] neg_lo:[1,0,0] neg_hi:[1,0,0]
	v_add_f32_e32 v8, v8, v9
	v_pk_mul_f32 v[20:21], v[10:11], v[10:11]
	v_cmp_gt_f32_e32 vcc, s71, v25
	v_add_f32_e32 v8, v8, v20
	v_add_f32_e32 v8, v8, v21
	s_nop 1
	v_mov_b32_dpp v9, v8 quad_perm:[1,0,3,2] row_mask:0xf bank_mask:0xf
	v_mul_f32_e32 v20, 0x4b800000, v25
	v_cndmask_b32_e32 v20, v25, v20, vcc
	v_rsq_f32_e32 v20, v20
	ds_write_b16 v115, v24 offset:3184
	s_waitcnt lgkmcnt(0)
	v_add_f32_e32 v8, v8, v9
	s_nop 1
	v_mov_b32_dpp v9, v8 quad_perm:[2,3,0,1] row_mask:0xf bank_mask:0xf
	v_mul_f32_e32 v21, 0x45800000, v20
	v_cndmask_b32_e32 v20, v20, v21, vcc
	v_mul_f32_e32 v6, v6, v20
	v_mul_f32_e32 v6, v51, v6
	s_waitcnt lgkmcnt(0)
	v_add_f32_e32 v8, v8, v9
	s_nop 1
	v_mov_b32_dpp v9, v8 row_half_mirror row_mask:0xf bank_mask:0xf
	s_nop 0
	v_cvt_pk_bf16_f32 v6, v6, v6
	ds_write_b16 v115, v6 offset:4352
	v_mul_f32_e32 v6, v7, v20
	v_mul_f32_e32 v6, v50, v6
	s_waitcnt lgkmcnt(0)
	v_add_f32_e32 v7, v8, v9
	s_nop 1
	v_mov_b32_dpp v8, v7 row_mirror row_mask:0xf bank_mask:0xf
	s_nop 0
	v_cvt_pk_bf16_f32 v6, v6, v6
	ds_write_b16 v115, v6 offset:4416
	v_mul_f32_e32 v6, v22, v20
	v_mul_f32_e32 v6, v19, v6
	s_waitcnt lgkmcnt(0)
	v_add_f32_e32 v7, v7, v8
	ds_bpermute_b32 v8, v3, v7
	s_nop 0
	v_cvt_pk_bf16_f32 v6, v6, v6
	ds_write_b16 v115, v6 offset:4480
	v_mul_f32_e32 v24, v23, v20
	v_mov_b32_e32 v9, v96
	s_waitcnt lgkmcnt(0)
	v_add_f32_e32 v6, v7, v8
	v_fmamk_f32 v6, v6, 0x3c000000, v187
	v_mul_f32_e32 v7, 0x4b800000, v6
	v_cmp_gt_f32_e32 vcc, s71, v6
	v_mov_b32_e32 v8, v92
	v_mov_b32_e32 v20, v44
	v_cndmask_b32_e32 v6, v6, v7, vcc
	v_rsq_f32_e32 v25, v6
	v_mov_b32_e32 v6, v12
	v_mov_b32_e32 v7, v60
	v_pk_mul_f32 v[6:7], v[6:7], v[132:133] op_sel_hi:[1,0]
	v_mov_b32_e32 v21, v28
	v_pk_fma_f32 v[6:7], v[188:189], v[6:7], v[8:9] neg_lo:[1,0,0] neg_hi:[1,0,0]
	v_pk_mul_f32 v[20:21], v[20:21], v[132:133] op_sel_hi:[1,0]
	v_mov_b32_e32 v22, v84
	v_mov_b32_e32 v23, v88
	v_pk_mul_f32 v[8:9], v[6:7], v[6:7]
	v_pk_fma_f32 v[20:21], v[188:189], v[20:21], v[22:23] neg_lo:[1,0,0] neg_hi:[1,0,0]
	v_add_f32_e32 v8, v8, v9
	v_pk_mul_f32 v[22:23], v[20:21], v[20:21]
	v_mul_f32_e32 v12, v18, v24
	v_add_f32_e32 v8, v8, v22
	v_add_f32_e32 v8, v8, v23
	s_nop 1
	v_mov_b32_dpp v9, v8 quad_perm:[1,0,3,2] row_mask:0xf bank_mask:0xf
	s_nop 0
	v_cvt_pk_bf16_f32 v12, v12, v12
	ds_write_b16 v115, v12 offset:4544
	v_mul_f32_e32 v12, 0x45800000, v25
	v_cndmask_b32_e32 v12, v25, v12, vcc
	s_waitcnt lgkmcnt(0)
; __device__ __forceinline__ u16 f2bf(float f) { return (u16)(cvtpk(f, f) & 0xffffu); }
; __device__ __forceinline__ void phase3(const Params& p, char* shm) {
;     ...
;     for (int r = 0; r < 16; ++r) {
;       float ss = 0.f;
; #pragma unroll
;       for (int d0 = 0; d0 < 4; ++d0) ss += o[d0][r] * o[d0][r];
;       ss += __shfl_xor(ss, 1); ss += __shfl_xor(ss, 2); ss += __shfl_xor(ss, 4); ss += __shfl_xor(ss, 8); ss += __shfl_xor(ss, 16);
;       const float rstd = rsqrtf(ss * (1.f / 128.f) + 1e-6f);
; #pragma unroll
;       for (int d0 = 0; d0 < 4; ++d0) *(u16*)(otb + (((r & 3) + 8 * (r >> 2)) * OT_LD + d0 * 32) * 2) = f2bf(o[d0][r] * rstd * sw[d0]);
;     }
	v_add_f32_e32 v8, v8, v9
	s_nop 1
	v_mov_b32_dpp v9, v8 quad_perm:[2,3,0,1] row_mask:0xf bank_mask:0xf
	v_mul_f32_e32 v4, v4, v12
	v_mul_f32_e32 v4, v51, v4
	s_nop 0
	v_cvt_pk_bf16_f32 v4, v4, v4
	ds_write_b16 v115, v4 offset:4624
	s_waitcnt lgkmcnt(0)
	v_add_f32_e32 v8, v8, v9
	s_nop 1
	v_mov_b32_dpp v9, v8 row_half_mirror row_mask:0xf bank_mask:0xf
	v_mul_f32_e32 v4, v5, v12
	v_mul_f32_e32 v4, v50, v4
	s_nop 0
	v_cvt_pk_bf16_f32 v4, v4, v4
	ds_write_b16 v115, v4 offset:4688
	s_waitcnt lgkmcnt(0)
	v_add_f32_e32 v5, v8, v9
	s_nop 1
	v_mov_b32_dpp v8, v5 row_mirror row_mask:0xf bank_mask:0xf
	v_mul_f32_e32 v4, v10, v12
	v_mul_f32_e32 v4, v19, v4
	s_nop 0
	v_cvt_pk_bf16_f32 v4, v4, v4
	ds_write_b16 v115, v4 offset:4752
	s_waitcnt lgkmcnt(0)
	v_add_f32_e32 v5, v5, v8
	ds_bpermute_b32 v8, v3, v5
	v_mul_f32_e32 v4, v11, v12
	v_mul_f32_e32 v4, v18, v4
	s_nop 0
	v_cvt_pk_bf16_f32 v22, v4, v4
	v_mov_b32_e32 v60, v13
	s_waitcnt lgkmcnt(0)
	v_add_f32_e32 v4, v5, v8
	v_fmamk_f32 v23, v4, 0x3c000000, v187
	v_pk_mul_f32 v[4:5], v[60:61], v[130:131] op_sel_hi:[1,0]
	v_mov_b32_e32 v96, v93
	v_mov_b32_e32 v28, v45
	v_pk_fma_f32 v[4:5], v[188:189], v[4:5], v[96:97] neg_lo:[1,0,0] neg_hi:[1,0,0]
	v_pk_mul_f32 v[10:11], v[28:29], v[130:131] op_sel_hi:[1,0]
	v_mov_b32_e32 v88, v85
	v_pk_mul_f32 v[8:9], v[4:5], v[4:5]
	v_pk_fma_f32 v[10:11], v[188:189], v[10:11], v[88:89] neg_lo:[1,0,0] neg_hi:[1,0,0]
	v_add_f32_e32 v8, v8, v9
	v_pk_mul_f32 v[12:13], v[10:11], v[10:11]
	v_cmp_gt_f32_e32 vcc, s71, v23
	v_add_f32_e32 v8, v8, v12
	v_add_f32_e32 v8, v8, v13
	s_nop 1
	v_mov_b32_dpp v9, v8 quad_perm:[1,0,3,2] row_mask:0xf bank_mask:0xf
	v_mul_f32_e32 v12, 0x4b800000, v23
	v_cndmask_b32_e32 v12, v23, v12, vcc
	v_rsq_f32_e32 v12, v12
	ds_write_b16 v115, v22 offset:4816
	s_waitcnt lgkmcnt(0)
	v_add_f32_e32 v8, v8, v9
	s_nop 1
	v_mov_b32_dpp v9, v8 quad_perm:[2,3,0,1] row_mask:0xf bank_mask:0xf
	v_mul_f32_e32 v13, 0x45800000, v12
	v_cndmask_b32_e32 v12, v12, v13, vcc
	v_mul_f32_e32 v6, v6, v12
	v_mul_f32_e32 v6, v51, v6
	s_waitcnt lgkmcnt(0)
	v_add_f32_e32 v8, v8, v9
	s_nop 1
	v_mov_b32_dpp v9, v8 row_half_mirror row_mask:0xf bank_mask:0xf
	s_nop 0
	v_cvt_pk_bf16_f32 v6, v6, v6
	ds_write_b16 v115, v6 offset:4896
	v_mul_f32_e32 v6, v7, v12
	v_mul_f32_e32 v6, v50, v6
	s_waitcnt lgkmcnt(0)
	v_add_f32_e32 v7, v8, v9
	s_nop 1
	v_mov_b32_dpp v8, v7 row_mirror row_mask:0xf bank_mask:0xf
	s_nop 0
	v_cvt_pk_bf16_f32 v6, v6, v6
	ds_write_b16 v115, v6 offset:4960
	v_mul_f32_e32 v6, v20, v12
	v_mul_f32_e32 v6, v19, v6
	s_waitcnt lgkmcnt(0)
	v_add_f32_e32 v7, v7, v8
	ds_bpermute_b32 v8, v3, v7
	s_nop 0
	v_cvt_pk_bf16_f32 v6, v6, v6
	ds_write_b16 v115, v6 offset:5024
	v_mul_f32_e32 v22, v21, v12
	v_mov_b32_e32 v9, v78
	s_waitcnt lgkmcnt(0)
	v_add_f32_e32 v6, v7, v8
	v_fmamk_f32 v6, v6, 0x3c000000, v187
	v_mul_f32_e32 v7, 0x4b800000, v6
	v_cmp_gt_f32_e32 vcc, s71, v6
	v_mov_b32_e32 v8, v74
	v_mov_b32_e32 v12, v46
	v_cndmask_b32_e32 v6, v6, v7, vcc
	v_rsq_f32_e32 v23, v6
	v_mov_b32_e32 v6, v14
	v_mov_b32_e32 v7, v62
	v_pk_mul_f32 v[6:7], v[6:7], v[118:119] op_sel_hi:[1,0]
	v_mov_b32_e32 v13, v30
	v_pk_fma_f32 v[6:7], v[188:189], v[6:7], v[8:9] neg_lo:[1,0,0] neg_hi:[1,0,0]
	v_pk_mul_f32 v[12:13], v[12:13], v[118:119] op_sel_hi:[1,0]
	v_mov_b32_e32 v20, v66
	v_mov_b32_e32 v21, v70
	v_pk_mul_f32 v[8:9], v[6:7], v[6:7]
	v_pk_fma_f32 v[12:13], v[188:189], v[12:13], v[20:21] neg_lo:[1,0,0] neg_hi:[1,0,0]
	v_add_f32_e32 v8, v8, v9
	v_pk_mul_f32 v[20:21], v[12:13], v[12:13]
	v_mul_f32_e32 v14, v18, v22
	v_add_f32_e32 v8, v8, v20
	v_add_f32_e32 v8, v8, v21
	s_nop 1
	v_mov_b32_dpp v9, v8 quad_perm:[1,0,3,2] row_mask:0xf bank_mask:0xf
	s_nop 0
	v_cvt_pk_bf16_f32 v14, v14, v14
	ds_write_b16 v115, v14 offset:5088
	v_mul_f32_e32 v14, 0x45800000, v23
	v_cndmask_b32_e32 v14, v23, v14, vcc
	s_waitcnt lgkmcnt(0)
	v_add_f32_e32 v8, v8, v9
	s_nop 1
	v_mov_b32_dpp v9, v8 quad_perm:[2,3,0,1] row_mask:0xf bank_mask:0xf
	v_mul_f32_e32 v4, v4, v14
	v_mul_f32_e32 v4, v51, v4
	s_nop 0
	v_cvt_pk_bf16_f32 v4, v4, v4
	ds_write_b16 v115, v4 offset:5168
	s_waitcnt lgkmcnt(0)
	v_add_f32_e32 v8, v8, v9
	s_nop 1
	v_mov_b32_dpp v9, v8 row_half_mirror row_mask:0xf bank_mask:0xf
	v_mul_f32_e32 v4, v5, v14
	v_mul_f32_e32 v4, v50, v4
	s_nop 0
	v_cvt_pk_bf16_f32 v4, v4, v4
	ds_write_b16 v115, v4 offset:5232
	s_waitcnt lgkmcnt(0)
	v_add_f32_e32 v5, v8, v9
	s_nop 1
	v_mov_b32_dpp v8, v5 row_mirror row_mask:0xf bank_mask:0xf
	v_mul_f32_e32 v4, v10, v14
	v_mul_f32_e32 v4, v19, v4
	s_nop 0
	v_cvt_pk_bf16_f32 v4, v4, v4
	ds_write_b16 v115, v4 offset:5296
	s_waitcnt lgkmcnt(0)
	v_add_f32_e32 v5, v5, v8
	ds_bpermute_b32 v8, v3, v5
	v_mul_f32_e32 v4, v11, v14
	v_mul_f32_e32 v4, v18, v4
	s_nop 0
	v_cvt_pk_bf16_f32 v20, v4, v4
	v_mov_b32_e32 v62, v15
	s_waitcnt lgkmcnt(0)
	v_add_f32_e32 v4, v5, v8
	v_fmamk_f32 v21, v4, 0x3c000000, v187
	v_pk_mul_f32 v[4:5], v[62:63], v[114:115] op_sel_hi:[1,0]
	v_mov_b32_e32 v78, v75
	v_mov_b32_e32 v30, v47
	v_pk_fma_f32 v[4:5], v[188:189], v[4:5], v[78:79] neg_lo:[1,0,0] neg_hi:[1,0,0]
	v_pk_mul_f32 v[10:11], v[30:31], v[114:115] op_sel_hi:[1,0]
	v_mov_b32_e32 v70, v67
	v_pk_mul_f32 v[8:9], v[4:5], v[4:5]
	v_pk_fma_f32 v[10:11], v[188:189], v[10:11], v[70:71] neg_lo:[1,0,0] neg_hi:[1,0,0]
	v_add_f32_e32 v8, v8, v9
	v_pk_mul_f32 v[14:15], v[10:11], v[10:11]
	v_cmp_gt_f32_e32 vcc, s71, v21
	v_add_f32_e32 v8, v8, v14
	v_add_f32_e32 v8, v8, v15
	s_nop 1
	v_mov_b32_dpp v9, v8 quad_perm:[1,0,3,2] row_mask:0xf bank_mask:0xf
	v_mul_f32_e32 v14, 0x4b800000, v21
	v_cndmask_b32_e32 v14, v21, v14, vcc
	v_rsq_f32_e32 v14, v14
	ds_write_b16 v115, v20 offset:5360
	s_waitcnt lgkmcnt(0)
; __device__ __forceinline__ u16 f2bf(float f) { return (u16)(cvtpk(f, f) & 0xffffu); }
; __device__ __forceinline__ void phase3(const Params& p, char* shm) {
;     ...
;     for (int r = 0; r < 16; ++r) {
;       float ss = 0.f;
; #pragma unroll
;       for (int d0 = 0; d0 < 4; ++d0) ss += o[d0][r] * o[d0][r];
;       ss += __shfl_xor(ss, 1); ss += __shfl_xor(ss, 2); ss += __shfl_xor(ss, 4); ss += __shfl_xor(ss, 8); ss += __shfl_xor(ss, 16);
;       const float rstd = rsqrtf(ss * (1.f / 128.f) + 1e-6f);
; #pragma unroll
;       for (int d0 = 0; d0 < 4; ++d0) *(u16*)(otb + (((r & 3) + 8 * (r >> 2)) * OT_LD + d0 * 32) * 2) = f2bf(o[d0][r] * rstd * sw[d0]);
;     }
;     __syncthreads();
	v_add_f32_e32 v8, v8, v9
	s_nop 1
	v_mov_b32_dpp v9, v8 quad_perm:[2,3,0,1] row_mask:0xf bank_mask:0xf
	v_mul_f32_e32 v15, 0x45800000, v14
	v_cndmask_b32_e32 v14, v14, v15, vcc
	v_mul_f32_e32 v6, v6, v14
	v_mul_f32_e32 v6, v51, v6
	s_waitcnt lgkmcnt(0)
	v_add_f32_e32 v8, v8, v9
	s_nop 1
	v_mov_b32_dpp v9, v8 row_half_mirror row_mask:0xf bank_mask:0xf
	s_nop 0
	v_cvt_pk_bf16_f32 v6, v6, v6
	ds_write_b16 v115, v6 offset:6528
	v_mul_f32_e32 v6, v7, v14
	v_mul_f32_e32 v6, v50, v6
	s_waitcnt lgkmcnt(0)
	v_add_f32_e32 v7, v8, v9
	s_nop 1
	v_mov_b32_dpp v8, v7 row_mirror row_mask:0xf bank_mask:0xf
	s_nop 0
	v_cvt_pk_bf16_f32 v6, v6, v6
	ds_write_b16 v115, v6 offset:6592
	v_mul_f32_e32 v6, v12, v14
	v_mul_f32_e32 v6, v19, v6
	s_waitcnt lgkmcnt(0)
	v_add_f32_e32 v7, v7, v8
	ds_bpermute_b32 v8, v3, v7
	s_nop 0
	v_cvt_pk_bf16_f32 v6, v6, v6
	ds_write_b16 v115, v6 offset:6656
	v_mul_f32_e32 v20, v13, v14
	v_mov_b32_e32 v9, v80
	s_waitcnt lgkmcnt(0)
	v_add_f32_e32 v6, v7, v8
	v_fmamk_f32 v6, v6, 0x3c000000, v187
	v_mul_f32_e32 v7, 0x4b800000, v6
	v_cmp_gt_f32_e32 vcc, s71, v6
	v_mov_b32_e32 v8, v76
	v_mov_b32_e32 v12, v48
	v_cndmask_b32_e32 v6, v6, v7, vcc
	v_rsq_f32_e32 v21, v6
	v_mov_b32_e32 v6, v16
	v_mov_b32_e32 v7, v64
	v_pk_mul_f32 v[6:7], v[6:7], v[34:35] op_sel_hi:[1,0]
	v_mov_b32_e32 v13, v32
	v_pk_fma_f32 v[6:7], v[188:189], v[6:7], v[8:9] neg_lo:[1,0,0] neg_hi:[1,0,0]
	v_pk_mul_f32 v[12:13], v[12:13], v[34:35] op_sel_hi:[1,0]
	v_mov_b32_e32 v14, v68
	v_mov_b32_e32 v15, v72
	v_pk_mul_f32 v[8:9], v[6:7], v[6:7]
	v_pk_fma_f32 v[12:13], v[188:189], v[12:13], v[14:15] neg_lo:[1,0,0] neg_hi:[1,0,0]
	v_add_f32_e32 v8, v8, v9
	v_pk_mul_f32 v[14:15], v[12:13], v[12:13]
	v_mov_b32_e32 v64, v17
	v_add_f32_e32 v8, v8, v14
	v_add_f32_e32 v8, v8, v15
	s_nop 1
	v_mov_b32_dpp v9, v8 quad_perm:[1,0,3,2] row_mask:0xf bank_mask:0xf
	v_mul_f32_e32 v14, v18, v20
	s_nop 0
	v_cvt_pk_bf16_f32 v14, v14, v14
	ds_write_b16 v115, v14 offset:6720
	v_mul_f32_e32 v14, 0x45800000, v21
	s_waitcnt lgkmcnt(0)
	v_add_f32_e32 v8, v8, v9
	s_nop 1
	v_mov_b32_dpp v9, v8 quad_perm:[2,3,0,1] row_mask:0xf bank_mask:0xf
	v_cndmask_b32_e32 v14, v21, v14, vcc
	v_mul_f32_e32 v4, v4, v14
	v_mul_f32_e32 v4, v51, v4
	s_nop 0
	v_cvt_pk_bf16_f32 v4, v4, v4
	s_waitcnt lgkmcnt(0)
	v_add_f32_e32 v8, v8, v9
	s_nop 1
	v_mov_b32_dpp v9, v8 row_half_mirror row_mask:0xf bank_mask:0xf
	ds_write_b16 v115, v4 offset:6800
	v_mul_f32_e32 v4, v5, v14
	v_mul_f32_e32 v4, v50, v4
	s_nop 0
	v_cvt_pk_bf16_f32 v4, v4, v4
	s_waitcnt lgkmcnt(0)
	v_add_f32_e32 v5, v8, v9
	s_nop 1
	v_mov_b32_dpp v8, v5 row_mirror row_mask:0xf bank_mask:0xf
	ds_write_b16 v115, v4 offset:6864
	v_mul_f32_e32 v4, v10, v14
	v_mul_f32_e32 v4, v19, v4
	s_nop 0
	v_cvt_pk_bf16_f32 v4, v4, v4
	s_waitcnt lgkmcnt(0)
	v_add_f32_e32 v5, v5, v8
	ds_bpermute_b32 v8, v3, v5
	ds_write_b16 v115, v4 offset:6928
	v_mul_f32_e32 v4, v11, v14
	v_mul_f32_e32 v4, v18, v4
	s_nop 0
	v_cvt_pk_bf16_f32 v16, v4, v4
	s_waitcnt lgkmcnt(0)
	v_add_f32_e32 v4, v5, v8
	v_fmamk_f32 v20, v4, 0x3c000000, v187
	v_pk_mul_f32 v[4:5], v[64:65], v[2:3] op_sel_hi:[1,0]
	v_mov_b32_e32 v80, v77
	v_mov_b32_e32 v32, v49
	v_pk_fma_f32 v[4:5], v[188:189], v[4:5], v[80:81] neg_lo:[1,0,0] neg_hi:[1,0,0]
	v_pk_mul_f32 v[10:11], v[32:33], v[2:3] op_sel_hi:[1,0]
	v_mov_b32_e32 v72, v69
	v_pk_mul_f32 v[8:9], v[4:5], v[4:5]
	v_pk_fma_f32 v[10:11], v[188:189], v[10:11], v[72:73] neg_lo:[1,0,0] neg_hi:[1,0,0]
	v_add_f32_e32 v2, v8, v9
	v_pk_mul_f32 v[14:15], v[10:11], v[10:11]
	v_mul_f32_e32 v9, 0x4b800000, v20
	v_add_f32_e32 v2, v2, v14
	v_add_f32_e32 v2, v2, v15
	s_nop 1
	v_mov_b32_dpp v8, v2 quad_perm:[1,0,3,2] row_mask:0xf bank_mask:0xf
	v_cmp_gt_f32_e32 vcc, s71, v20
	ds_write_b16 v115, v16 offset:6992
	s_waitcnt lgkmcnt(0)
	v_add_f32_e32 v2, v2, v8
	s_nop 1
	v_mov_b32_dpp v8, v2 quad_perm:[2,3,0,1] row_mask:0xf bank_mask:0xf
	v_cndmask_b32_e32 v9, v20, v9, vcc
	v_rsq_f32_e32 v9, v9
	s_waitcnt lgkmcnt(0)
	v_add_f32_e32 v2, v2, v8
	s_nop 1
	v_mov_b32_dpp v8, v2 row_half_mirror row_mask:0xf bank_mask:0xf
	v_mul_f32_e32 v14, 0x45800000, v9
	v_cndmask_b32_e32 v9, v9, v14, vcc
	v_mul_f32_e32 v6, v6, v9
	v_mul_f32_e32 v6, v51, v6
	s_nop 0
	v_cvt_pk_bf16_f32 v6, v6, v6
	s_waitcnt lgkmcnt(0)
	v_add_f32_e32 v2, v2, v8
	ds_write_b16 v115, v6 offset:7072
	v_mul_f32_e32 v6, v7, v9
	s_nop 1
	v_mov_b32_dpp v7, v2 row_mirror row_mask:0xf bank_mask:0xf
	v_mul_f32_e32 v6, v50, v6
	s_nop 0
	v_cvt_pk_bf16_f32 v6, v6, v6
	ds_write_b16 v115, v6 offset:7136
	v_mul_f32_e32 v6, v12, v9
	s_waitcnt lgkmcnt(0)
	v_add_f32_e32 v2, v2, v7
	ds_bpermute_b32 v3, v3, v2
	v_mul_f32_e32 v6, v19, v6
	s_nop 0
	v_cvt_pk_bf16_f32 v6, v6, v6
	ds_write_b16 v115, v6 offset:7200
	v_mul_f32_e32 v6, v13, v9
	s_waitcnt lgkmcnt(0)
	v_add_f32_e32 v2, v2, v3
	v_fmamk_f32 v2, v2, 0x3c000000, v187
	v_mul_f32_e32 v3, 0x4b800000, v2
	v_cmp_gt_f32_e32 vcc, s71, v2
	s_nop 1
	v_cndmask_b32_e32 v2, v2, v3, vcc
	v_rsq_f32_e32 v2, v2
	v_mul_f32_e32 v3, v18, v6
	s_nop 0
	v_cvt_pk_bf16_f32 v3, v3, v3
	ds_write_b16 v115, v3 offset:7264
	v_mul_f32_e32 v3, 0x45800000, v2
	v_cndmask_b32_e32 v2, v2, v3, vcc
	v_mul_f32_e32 v3, v4, v2
	v_mul_f32_e32 v3, v51, v3
	s_nop 0
	v_cvt_pk_bf16_f32 v3, v3, v3
	ds_write_b16 v115, v3 offset:7344
	v_mul_f32_e32 v3, v5, v2
	v_mul_f32_e32 v3, v50, v3
	s_nop 0
	v_cvt_pk_bf16_f32 v3, v3, v3
	ds_write_b16 v115, v3 offset:7408
	v_mul_f32_e32 v3, v10, v2
	v_mul_f32_e32 v2, v11, v2
	v_mul_f32_e32 v3, v19, v3
	v_mul_f32_e32 v2, v18, v2
	v_cmp_gt_i32_e32 vcc, s72, v131
	s_nop 0
	v_cvt_pk_bf16_f32 v3, v3, v3
	ds_write_b16 v115, v3 offset:7472
	s_nop 0
	v_cvt_pk_bf16_f32 v2, v2, v2
	ds_write_b16 v115, v2 offset:7536
	s_waitcnt lgkmcnt(0)
	s_barrier
; __device__ __forceinline__ float bflo(unsigned v) { return __uint_as_float(v << 16); }
; __device__ __forceinline__ float bfhi(unsigned v) { return __uint_as_float(v & 0xffff0000u); }
; __device__ __forceinline__ void phase3(const Params& p, char* shm) {
;     ...
;     { const u16* zsrc = Zb + t0 * AW + h * 128; u16* bdst = Bin + t0 * AW + h * 128;
; #pragma unroll 2
;       for (int id = tid; id < 256 * 16; id += NTHR) {
;         const int row = id >> 4, c = id & 15;
;         const u32x4 ov = *reinterpret_cast<const u32x4*>(shm + (row * OT_LD + c * 8) * 2);
;         const u32x4 zv = *reinterpret_cast<const u32x4*>(zsrc + (size_t)row * AW + c * 8);
;         u32x4 w;
; #pragma unroll
;         for (int q = 0; q < 4; ++q) w[q] = cvtpk(bflo(ov[q]) * bflo(zv[q]), bfhi(ov[q]) * bfhi(zv[q]));
;         *reinterpret_cast<u32x4*>(bdst + (size_t)row * AW + c * 8) = w;
;       }
;     }
	s_and_saveexec_b64 s[0:1], vcc
	s_cbranch_execz .LBB0_322
	s_add_u32 s4, s79, s18
	s_addc_u32 s5, s80, s19
	s_add_u32 s4, s4, s86
	s_addc_u32 s5, s5, 0
	s_add_u32 s6, s81, s18
	s_addc_u32 s7, s82, s19
	s_add_u32 s6, s6, s86
	s_addc_u32 s7, s7, 0
	v_lshlrev_b32_e32 v2, 3, v131
	v_lshrrev_b32_e32 v52, 4, v131
	v_and_b32_e32 v53, 15, v131
	v_lshlrev_b32_e32 v54, 11, v52
	v_lshl_add_u32 v54, v53, 4, v54
	v_mul_u32_u24_e32 v52, 0x110, v52
	v_lshl_add_u32 v52, v53, 4, v52
	v_add_u32_e32 v55, 0x10000, v54
	v_add_u32_e32 v56, 0x20000, v54
	v_add_u32_e32 v57, 0x30000, v54
	v_add_u32_e32 v58, 0x40000, v54
	v_add_u32_e32 v59, 0x50000, v54
	v_add_u32_e32 v60, 0x60000, v54
	v_add_u32_e32 v61, 0x70000, v54
	global_load_dwordx4 v[4:7], v54, s[4:5]
	global_load_dwordx4 v[8:11], v55, s[4:5]
	global_load_dwordx4 v[12:15], v56, s[4:5]
	global_load_dwordx4 v[16:19], v57, s[4:5]
	global_load_dwordx4 v[20:23], v58, s[4:5]
	global_load_dwordx4 v[24:27], v59, s[4:5]
	global_load_dwordx4 v[28:31], v60, s[4:5]
	global_load_dwordx4 v[32:35], v61, s[4:5]
	ds_read_b128 v[36:39], v52
	ds_read_b128 v[40:43], v52 offset:8704
	ds_read_b128 v[44:47], v52 offset:17408
	ds_read_b128 v[48:51], v52 offset:26112
	s_waitcnt vmcnt(7) lgkmcnt(3)
	v_lshlrev_b32_e32 v62, 16, v36
	v_lshlrev_b32_e32 v63, 16, v4
	v_and_b32_e32 v36, 0xffff0000, v36
	v_and_b32_e32 v4, 0xffff0000, v4
	v_mul_f32_e32 v62, v63, v62
	v_mul_f32_e32 v4, v4, v36
	v_cvt_pk_bf16_f32 v4, v62, v4
	v_lshlrev_b32_e32 v62, 16, v37
	v_lshlrev_b32_e32 v63, 16, v5
	v_and_b32_e32 v37, 0xffff0000, v37
	v_and_b32_e32 v5, 0xffff0000, v5
	v_mul_f32_e32 v62, v63, v62
	v_mul_f32_e32 v5, v5, v37
	v_cvt_pk_bf16_f32 v5, v62, v5
	v_lshlrev_b32_e32 v62, 16, v38
	v_lshlrev_b32_e32 v63, 16, v6
	v_and_b32_e32 v38, 0xffff0000, v38
	v_and_b32_e32 v6, 0xffff0000, v6
	v_mul_f32_e32 v62, v63, v62
	v_mul_f32_e32 v6, v6, v38
	v_cvt_pk_bf16_f32 v6, v62, v6
	v_lshlrev_b32_e32 v62, 16, v39
	v_lshlrev_b32_e32 v63, 16, v7
	v_and_b32_e32 v39, 0xffff0000, v39
	v_and_b32_e32 v7, 0xffff0000, v7
	v_mul_f32_e32 v62, v63, v62
	v_mul_f32_e32 v7, v7, v39
	v_cvt_pk_bf16_f32 v7, v62, v7
	global_store_dwordx4 v54, v[4:7], s[6:7]
	s_waitcnt vmcnt(7) lgkmcnt(2)
	v_lshlrev_b32_e32 v62, 16, v40
	v_lshlrev_b32_e32 v63, 16, v8
	v_and_b32_e32 v40, 0xffff0000, v40
	v_and_b32_e32 v8, 0xffff0000, v8
	v_mul_f32_e32 v62, v63, v62
	v_mul_f32_e32 v8, v8, v40
	v_cvt_pk_bf16_f32 v8, v62, v8
	v_lshlrev_b32_e32 v62, 16, v41
	v_lshlrev_b32_e32 v63, 16, v9
	v_and_b32_e32 v41, 0xffff0000, v41
	v_and_b32_e32 v9, 0xffff0000, v9
	v_mul_f32_e32 v62, v63, v62
	v_mul_f32_e32 v9, v9, v41
	v_cvt_pk_bf16_f32 v9, v62, v9
	v_lshlrev_b32_e32 v62, 16, v42
	v_lshlrev_b32_e32 v63, 16, v10
	v_and_b32_e32 v42, 0xffff0000, v42
	v_and_b32_e32 v10, 0xffff0000, v10
	v_mul_f32_e32 v62, v63, v62
	v_mul_f32_e32 v10, v10, v42
	v_cvt_pk_bf16_f32 v10, v62, v10
	v_lshlrev_b32_e32 v62, 16, v43
	v_lshlrev_b32_e32 v63, 16, v11
	v_and_b32_e32 v43, 0xffff0000, v43
	v_and_b32_e32 v11, 0xffff0000, v11
	v_mul_f32_e32 v62, v63, v62
	v_mul_f32_e32 v11, v11, v43
	v_cvt_pk_bf16_f32 v11, v62, v11
	global_store_dwordx4 v55, v[8:11], s[6:7]
	s_waitcnt vmcnt(7) lgkmcnt(1)
	v_lshlrev_b32_e32 v62, 16, v44
	v_lshlrev_b32_e32 v63, 16, v12
	v_and_b32_e32 v44, 0xffff0000, v44
	v_and_b32_e32 v12, 0xffff0000, v12
	v_mul_f32_e32 v62, v63, v62
	v_mul_f32_e32 v12, v12, v44
	v_cvt_pk_bf16_f32 v12, v62, v12
	v_lshlrev_b32_e32 v62, 16, v45
	v_lshlrev_b32_e32 v63, 16, v13
	v_and_b32_e32 v45, 0xffff0000, v45
	v_and_b32_e32 v13, 0xffff0000, v13
	v_mul_f32_e32 v62, v63, v62
	v_mul_f32_e32 v13, v13, v45
	v_cvt_pk_bf16_f32 v13, v62, v13
	v_lshlrev_b32_e32 v62, 16, v46
	v_lshlrev_b32_e32 v63, 16, v14
	v_and_b32_e32 v46, 0xffff0000, v46
	v_and_b32_e32 v14, 0xffff0000, v14
	v_mul_f32_e32 v62, v63, v62
	v_mul_f32_e32 v14, v14, v46
	v_cvt_pk_bf16_f32 v14, v62, v14
	v_lshlrev_b32_e32 v62, 16, v47
	v_lshlrev_b32_e32 v63, 16, v15
	v_and_b32_e32 v47, 0xffff0000, v47
	v_and_b32_e32 v15, 0xffff0000, v15
	v_mul_f32_e32 v62, v63, v62
	v_mul_f32_e32 v15, v15, v47
	v_cvt_pk_bf16_f32 v15, v62, v15
	global_store_dwordx4 v56, v[12:15], s[6:7]
	s_waitcnt vmcnt(7) lgkmcnt(0)
; __device__ __forceinline__ float bflo(unsigned v) { return __uint_as_float(v << 16); }
; __device__ __forceinline__ float bfhi(unsigned v) { return __uint_as_float(v & 0xffff0000u); }
; __device__ __forceinline__ void phase3(const Params& p, char* shm) {
;     ...
;     { const u16* zsrc = Zb + t0 * AW + h * 128; u16* bdst = Bin + t0 * AW + h * 128;
; #pragma unroll 2
;       for (int id = tid; id < 256 * 16; id += NTHR) {
;         const int row = id >> 4, c = id & 15;
;         const u32x4 ov = *reinterpret_cast<const u32x4*>(shm + (row * OT_LD + c * 8) * 2);
;         const u32x4 zv = *reinterpret_cast<const u32x4*>(zsrc + (size_t)row * AW + c * 8);
;         u32x4 w;
; #pragma unroll
;         for (int q = 0; q < 4; ++q) w[q] = cvtpk(bflo(ov[q]) * bflo(zv[q]), bfhi(ov[q]) * bfhi(zv[q]));
;         *reinterpret_cast<u32x4*>(bdst + (size_t)row * AW + c * 8) = w;
;       }
;     }
	v_lshlrev_b32_e32 v62, 16, v48
	v_lshlrev_b32_e32 v63, 16, v16
	v_and_b32_e32 v48, 0xffff0000, v48
	v_and_b32_e32 v16, 0xffff0000, v16
	v_mul_f32_e32 v62, v63, v62
	v_mul_f32_e32 v16, v16, v48
	v_cvt_pk_bf16_f32 v16, v62, v16
	v_lshlrev_b32_e32 v62, 16, v49
	v_lshlrev_b32_e32 v63, 16, v17
	v_and_b32_e32 v49, 0xffff0000, v49
	v_and_b32_e32 v17, 0xffff0000, v17
	v_mul_f32_e32 v62, v63, v62
	v_mul_f32_e32 v17, v17, v49
	v_cvt_pk_bf16_f32 v17, v62, v17
	v_lshlrev_b32_e32 v62, 16, v50
	v_lshlrev_b32_e32 v63, 16, v18
	v_and_b32_e32 v50, 0xffff0000, v50
	v_and_b32_e32 v18, 0xffff0000, v18
	v_mul_f32_e32 v62, v63, v62
	v_mul_f32_e32 v18, v18, v50
	v_cvt_pk_bf16_f32 v18, v62, v18
	v_lshlrev_b32_e32 v62, 16, v51
	v_lshlrev_b32_e32 v63, 16, v19
	v_and_b32_e32 v51, 0xffff0000, v51
	v_and_b32_e32 v19, 0xffff0000, v19
	v_mul_f32_e32 v62, v63, v62
	v_mul_f32_e32 v19, v19, v51
	v_cvt_pk_bf16_f32 v19, v62, v19
	global_store_dwordx4 v57, v[16:19], s[6:7]
	ds_read_b128 v[36:39], v52 offset:34816
	ds_read_b128 v[40:43], v52 offset:43520
	ds_read_b128 v[44:47], v52 offset:52224
	ds_read_b128 v[48:51], v52 offset:60928
	s_waitcnt vmcnt(7) lgkmcnt(3)
	v_lshlrev_b32_e32 v62, 16, v36
	v_lshlrev_b32_e32 v63, 16, v20
	v_and_b32_e32 v36, 0xffff0000, v36
	v_and_b32_e32 v20, 0xffff0000, v20
	v_mul_f32_e32 v62, v63, v62
	v_mul_f32_e32 v20, v20, v36
	v_cvt_pk_bf16_f32 v20, v62, v20
	v_lshlrev_b32_e32 v62, 16, v37
	v_lshlrev_b32_e32 v63, 16, v21
	v_and_b32_e32 v37, 0xffff0000, v37
	v_and_b32_e32 v21, 0xffff0000, v21
	v_mul_f32_e32 v62, v63, v62
	v_mul_f32_e32 v21, v21, v37
	v_cvt_pk_bf16_f32 v21, v62, v21
	v_lshlrev_b32_e32 v62, 16, v38
	v_lshlrev_b32_e32 v63, 16, v22
	v_and_b32_e32 v38, 0xffff0000, v38
	v_and_b32_e32 v22, 0xffff0000, v22
	v_mul_f32_e32 v62, v63, v62
	v_mul_f32_e32 v22, v22, v38
	v_cvt_pk_bf16_f32 v22, v62, v22
	v_lshlrev_b32_e32 v62, 16, v39
	v_lshlrev_b32_e32 v63, 16, v23
	v_and_b32_e32 v39, 0xffff0000, v39
	v_and_b32_e32 v23, 0xffff0000, v23
	v_mul_f32_e32 v62, v63, v62
	v_mul_f32_e32 v23, v23, v39
	v_cvt_pk_bf16_f32 v23, v62, v23
	global_store_dwordx4 v58, v[20:23], s[6:7]
	s_waitcnt vmcnt(7) lgkmcnt(2)
	v_lshlrev_b32_e32 v62, 16, v40
	v_lshlrev_b32_e32 v63, 16, v24
	v_and_b32_e32 v40, 0xffff0000, v40
	v_and_b32_e32 v24, 0xffff0000, v24
	v_mul_f32_e32 v62, v63, v62
	v_mul_f32_e32 v24, v24, v40
	v_cvt_pk_bf16_f32 v24, v62, v24
	v_lshlrev_b32_e32 v62, 16, v41
	v_lshlrev_b32_e32 v63, 16, v25
	v_and_b32_e32 v41, 0xffff0000, v41
	v_and_b32_e32 v25, 0xffff0000, v25
	v_mul_f32_e32 v62, v63, v62
	v_mul_f32_e32 v25, v25, v41
	v_cvt_pk_bf16_f32 v25, v62, v25
	v_lshlrev_b32_e32 v62, 16, v42
	v_lshlrev_b32_e32 v63, 16, v26
	v_and_b32_e32 v42, 0xffff0000, v42
	v_and_b32_e32 v26, 0xffff0000, v26
	v_mul_f32_e32 v62, v63, v62
	v_mul_f32_e32 v26, v26, v42
	v_cvt_pk_bf16_f32 v26, v62, v26
	v_lshlrev_b32_e32 v62, 16, v43
	v_lshlrev_b32_e32 v63, 16, v27
	v_and_b32_e32 v43, 0xffff0000, v43
	v_and_b32_e32 v27, 0xffff0000, v27
	v_mul_f32_e32 v62, v63, v62
	v_mul_f32_e32 v27, v27, v43
	v_cvt_pk_bf16_f32 v27, v62, v27
	global_store_dwordx4 v59, v[24:27], s[6:7]
	s_waitcnt vmcnt(7) lgkmcnt(1)
	v_lshlrev_b32_e32 v62, 16, v44
	v_lshlrev_b32_e32 v63, 16, v28
	v_and_b32_e32 v44, 0xffff0000, v44
	v_and_b32_e32 v28, 0xffff0000, v28
	v_mul_f32_e32 v62, v63, v62
	v_mul_f32_e32 v28, v28, v44
	v_cvt_pk_bf16_f32 v28, v62, v28
	v_lshlrev_b32_e32 v62, 16, v45
	v_lshlrev_b32_e32 v63, 16, v29
	v_and_b32_e32 v45, 0xffff0000, v45
	v_and_b32_e32 v29, 0xffff0000, v29
	v_mul_f32_e32 v62, v63, v62
	v_mul_f32_e32 v29, v29, v45
	v_cvt_pk_bf16_f32 v29, v62, v29
	v_lshlrev_b32_e32 v62, 16, v46
	v_lshlrev_b32_e32 v63, 16, v30
	v_and_b32_e32 v46, 0xffff0000, v46
	v_and_b32_e32 v30, 0xffff0000, v30
	v_mul_f32_e32 v62, v63, v62
	v_mul_f32_e32 v30, v30, v46
	v_cvt_pk_bf16_f32 v30, v62, v30
	v_lshlrev_b32_e32 v62, 16, v47
	v_lshlrev_b32_e32 v63, 16, v31
	v_and_b32_e32 v47, 0xffff0000, v47
	v_and_b32_e32 v31, 0xffff0000, v31
	v_mul_f32_e32 v62, v63, v62
	v_mul_f32_e32 v31, v31, v47
	v_cvt_pk_bf16_f32 v31, v62, v31
	global_store_dwordx4 v60, v[28:31], s[6:7]
	s_waitcnt vmcnt(7) lgkmcnt(0)
	v_lshlrev_b32_e32 v62, 16, v48
	v_lshlrev_b32_e32 v63, 16, v32
	v_and_b32_e32 v48, 0xffff0000, v48
	v_and_b32_e32 v32, 0xffff0000, v32
	v_mul_f32_e32 v62, v63, v62
	v_mul_f32_e32 v32, v32, v48
	v_cvt_pk_bf16_f32 v32, v62, v32
	v_lshlrev_b32_e32 v62, 16, v49
	v_lshlrev_b32_e32 v63, 16, v33
	v_and_b32_e32 v49, 0xffff0000, v49
	v_and_b32_e32 v33, 0xffff0000, v33
	v_mul_f32_e32 v62, v63, v62
	v_mul_f32_e32 v33, v33, v49
	v_cvt_pk_bf16_f32 v33, v62, v33
	v_lshlrev_b32_e32 v62, 16, v50
	v_lshlrev_b32_e32 v63, 16, v34
	v_and_b32_e32 v50, 0xffff0000, v50
	v_and_b32_e32 v34, 0xffff0000, v34
	v_mul_f32_e32 v62, v63, v62
	v_mul_f32_e32 v34, v34, v50
	v_cvt_pk_bf16_f32 v34, v62, v34
	v_lshlrev_b32_e32 v62, 16, v51
	v_lshlrev_b32_e32 v63, 16, v35
	v_and_b32_e32 v51, 0xffff0000, v51
	v_and_b32_e32 v35, 0xffff0000, v35
	v_mul_f32_e32 v62, v63, v62
	v_mul_f32_e32 v35, v35, v51
	v_cvt_pk_bf16_f32 v35, v62, v35
	global_store_dwordx4 v61, v[32:35], s[6:7]
	v_add_u32_e32 v131, 0x1000, v131
	v_and_b32_e32 v190, 0x78, v2
	v_lshlrev_b32_e32 v190, 1, v190
	v_add_u32_e32 v2, 0x8000, v2
	s_mov_b64 s[18:19], exec
	s_nop 1
	s_branch .LBB0_322
